# lnfold stack + fused LN epilogues: K-loop drain and its barrier moved below the issue of the residual/gate loads
# baseline (speedup 1.0000x reference)
.LBB0_333:
	v_readlane_b32 s6, v253, 9
	v_readlane_b32 s7, v253, 10
	s_lshl_b64 s[6:7], s[6:7], 2
	s_add_u32 s2, s18, s6
	s_addc_u32 s6, s19, s7
	s_add_u32 s62, s2, 0x100000
	s_addc_u32 s63, s6, 0
	s_lshl_b32 s2, s50, 2
	s_add_u32 s2, s62, s2
	s_addc_u32 s12, s63, 0
	s_lshl_b64 s[6:7], s[66:67], 2
	s_add_u32 s8, s8, s6
	s_addc_u32 s9, s9, s7
	s_add_u32 s6, s10, s6
	s_addc_u32 s7, s11, s7
	s_lshl_b32 s24, s82, 8
	v_mbcnt_lo_u32_b32 v0, -1, 0
	v_mbcnt_hi_u32_b32 v0, -1, v0
	s_lshl_b32 s11, s22, 8
	v_ashrrev_i32_e32 v130, 2, v0
	s_ashr_i32 s25, s24, 31
	s_ashr_i32 s10, s82, 3
	s_or_b32 s11, s11, s43
	v_and_b32_e32 v130, -4, v130
	s_lshl_b64 s[26:27], s[24:25], 11
	v_add_u32_e32 v180, s11, v130
	s_add_u32 s14, s28, s26
	v_and_or_b32 v196, v0, 15, s17
	s_addc_u32 s15, s29, s27
	v_ashrrev_i32_e32 v181, 31, v180
	v_ashrrev_i32_e32 v197, 31, v196
	v_or_b32_e32 v194, 16, v196
	v_lshl_add_u64 v[138:139], v[180:181], 1, s[14:15]
	v_lshlrev_b64 v[130:131], 11, v[196:197]
	v_ashrrev_i32_e32 v195, 31, v194
	v_or_b32_e32 v192, 32, v196
	v_add_u32_e32 v184, 0xa0, v196
	v_add_u32_e32 v188, 0x80, v196
	v_lshl_add_u64 v[142:143], v[138:139], 0, v[130:131]
	v_lshlrev_b64 v[130:131], 11, v[194:195]
	v_ashrrev_i32_e32 v193, 31, v192
	v_or_b32_e32 v190, 48, v196
	v_add_u32_e32 v186, 0x90, v196
	v_ashrrev_i32_e32 v185, 31, v184
	v_add_u32_e32 v182, 0xb0, v196
	s_mul_hi_i32 s11, s10, 0x2400
	s_mulk_i32 s10, 0x2400
	v_ashrrev_i32_e32 v189, 31, v188
	v_lshl_add_u64 v[144:145], v[138:139], 0, v[130:131]
	v_lshlrev_b64 v[130:131], 11, v[192:193]
	v_ashrrev_i32_e32 v191, 31, v190
	v_ashrrev_i32_e32 v187, 31, v186
	v_lshlrev_b64 v[152:153], 11, v[184:185]
	v_ashrrev_i32_e32 v183, 31, v182
	v_lshlrev_b64 v[140:141], 11, v[188:189]
	v_lshl_add_u64 v[146:147], v[138:139], 0, v[130:131]
	v_lshlrev_b64 v[130:131], 11, v[190:191]
	v_lshlrev_b64 v[150:151], 11, v[186:187]
	v_lshl_add_u64 v[162:163], v[138:139], 0, v[152:153]
	v_lshlrev_b64 v[152:153], 11, v[182:183]
	s_lshl_b64 s[28:29], s[10:11], 2
	v_lshl_add_u64 v[148:149], v[138:139], 0, v[130:131]
	v_lshl_add_u64 v[140:141], v[138:139], 0, v[140:141]
	v_lshl_add_u64 v[150:151], v[138:139], 0, v[150:151]
	v_lshl_add_u64 v[138:139], v[138:139], 0, v[152:153]
	s_add_u32 s10, s2, s28
	global_load_dwordx2 v[136:137], v[142:143], off
	global_load_dwordx2 v[134:135], v[144:145], off
	global_load_dwordx2 v[132:133], v[146:147], off
	global_load_dwordx2 v[224:225], v[140:141], off
	global_load_dwordx2 v[130:131], v[148:149], off
	global_load_dwordx2 v[222:223], v[150:151], off
	global_load_dwordx2 v[220:221], v[162:163], off
	global_load_dwordx2 v[218:219], v[138:139], off
	global_load_dwordx2 v[216:217], v[142:143], off offset:32
	global_load_dwordx2 v[214:215], v[144:145], off offset:32
	global_load_dwordx2 v[212:213], v[146:147], off offset:32
	global_load_dwordx2 v[210:211], v[148:149], off offset:32
	global_load_dwordx2 v[208:209], v[140:141], off offset:32
	global_load_dwordx2 v[206:207], v[150:151], off offset:32
	global_load_dwordx2 v[204:205], v[162:163], off offset:32
	global_load_dwordx2 v[202:203], v[138:139], off offset:32
	global_load_dwordx2 v[200:201], v[142:143], off offset:256
	global_load_dwordx2 v[176:177], v[144:145], off offset:256
	global_load_dwordx2 v[174:175], v[146:147], off offset:256
	global_load_dwordx2 v[172:173], v[148:149], off offset:256
	global_load_dwordx2 v[170:171], v[140:141], off offset:256
	global_load_dwordx2 v[168:169], v[150:151], off offset:256
	global_load_dwordx2 v[166:167], v[162:163], off offset:256
	global_load_dwordx2 v[164:165], v[138:139], off offset:256
	global_load_dwordx2 v[160:161], v[142:143], off offset:288
	global_load_dwordx2 v[158:159], v[144:145], off offset:288
	global_load_dwordx2 v[156:157], v[146:147], off offset:288
	global_load_dwordx2 v[154:155], v[148:149], off offset:288
	global_load_dwordx2 v[152:153], v[140:141], off offset:288
	s_nop 0
	global_load_dwordx2 v[150:151], v[150:151], off offset:288
	s_nop 0
	global_load_dwordx2 v[148:149], v[162:163], off offset:288
	global_load_dwordx2 v[146:147], v[138:139], off offset:288
	s_addc_u32 s11, s12, s29
	v_lshlrev_b64 v[162:163], 2, v[180:181]
	v_lshl_add_u64 v[198:199], s[10:11], 0, v[162:163]
	global_load_dwordx4 v[138:141], v[198:199], off
	global_load_dwordx4 v[232:235], v[198:199], off offset:64
	global_load_dwordx4 v[236:239], v[198:199], off offset:512
	global_load_dwordx4 v[240:243], v[198:199], off offset:576
	s_waitcnt vmcnt(0)
	s_barrier
	s_lshl_b32 s2, s53, 3
	s_mov_b32 s42, s50
	s_add_i32 s2, s2, 0
	v_pk_mul_f32 v[228:229], v[140:141], 0.5 op_sel_hi:[1, 0]
	v_pk_mul_f32 v[226:227], v[138:139], 0.5 op_sel_hi:[1, 0]
	v_cvt_f32_f16_e32 v138, v137
	v_cvt_f32_f16_sdwa v139, v137 dst_sel:DWORD dst_unused:UNUSED_PAD src0_sel:WORD_1
	v_cvt_f32_f16_e32 v140, v136
	v_cvt_f32_f16_sdwa v141, v136 dst_sel:DWORD dst_unused:UNUSED_PAD src0_sel:WORD_1
	v_pk_mul_f32 v[138:139], v[138:139], s[90:91] op_sel_hi:[1, 0]
	s_nop 0
	v_pk_fma_f32 v[144:145], v[128:129], v[228:229], v[138:139]
	v_pk_mul_f32 v[136:137], v[140:141], s[90:91] op_sel_hi:[1, 0]
	v_cvt_f32_f16_e32 v128, v134
	v_pk_fma_f32 v[142:143], v[126:127], v[226:227], v[136:137]
	v_cvt_f32_f16_e32 v126, v135
	v_cvt_f32_f16_sdwa v127, v135 dst_sel:DWORD dst_unused:UNUSED_PAD src0_sel:WORD_1
	v_cvt_f32_f16_sdwa v129, v134 dst_sel:DWORD dst_unused:UNUSED_PAD src0_sel:WORD_1
	v_pk_mul_f32 v[126:127], v[126:127], s[90:91] op_sel_hi:[1, 0]
	v_pk_mul_f32 v[128:129], v[128:129], s[90:91] op_sel_hi:[1, 0]
	v_pk_fma_f32 v[140:141], v[124:125], v[228:229], v[126:127]
	v_pk_fma_f32 v[138:139], v[122:123], v[226:227], v[128:129]
	v_cvt_f32_f16_e32 v122, v133
	v_cvt_f32_f16_sdwa v123, v133 dst_sel:DWORD dst_unused:UNUSED_PAD src0_sel:WORD_1
	v_cvt_f32_f16_e32 v124, v132
	v_cvt_f32_f16_sdwa v125, v132 dst_sel:DWORD dst_unused:UNUSED_PAD src0_sel:WORD_1
	v_pk_mul_f32 v[122:123], v[122:123], s[90:91] op_sel_hi:[1, 0]
	v_pk_mul_f32 v[124:125], v[124:125], s[90:91] op_sel_hi:[1, 0]
	v_pk_fma_f32 v[136:137], v[120:121], v[228:229], v[122:123]
	v_pk_fma_f32 v[134:135], v[118:119], v[226:227], v[124:125]
	v_cvt_f32_f16_e32 v118, v131
	v_cvt_f32_f16_sdwa v119, v131 dst_sel:DWORD dst_unused:UNUSED_PAD src0_sel:WORD_1
	v_cvt_f32_f16_e32 v120, v130
	v_cvt_f32_f16_sdwa v121, v130 dst_sel:DWORD dst_unused:UNUSED_PAD src0_sel:WORD_1
	v_pk_mul_f32 v[118:119], v[118:119], s[90:91] op_sel_hi:[1, 0]
	v_pk_mul_f32 v[120:121], v[120:121], s[90:91] op_sel_hi:[1, 0]
	v_pk_fma_f32 v[132:133], v[116:117], v[228:229], v[118:119]
	v_pk_fma_f32 v[130:131], v[114:115], v[226:227], v[120:121]
	v_cvt_f32_f16_e32 v114, v225
	v_cvt_f32_f16_sdwa v115, v225 dst_sel:DWORD dst_unused:UNUSED_PAD src0_sel:WORD_1
	v_cvt_f32_f16_e32 v116, v224
	v_cvt_f32_f16_sdwa v117, v224 dst_sel:DWORD dst_unused:UNUSED_PAD src0_sel:WORD_1
	v_pk_mul_f32 v[114:115], v[114:115], s[90:91] op_sel_hi:[1, 0]
	v_pk_mul_f32 v[116:117], v[116:117], s[90:91] op_sel_hi:[1, 0]
	v_pk_fma_f32 v[128:129], v[112:113], v[228:229], v[114:115]
	v_pk_fma_f32 v[126:127], v[110:111], v[226:227], v[116:117]
	v_cvt_f32_f16_e32 v110, v223
	v_cvt_f32_f16_sdwa v111, v223 dst_sel:DWORD dst_unused:UNUSED_PAD src0_sel:WORD_1
	v_cvt_f32_f16_e32 v112, v222
	v_cvt_f32_f16_sdwa v113, v222 dst_sel:DWORD dst_unused:UNUSED_PAD src0_sel:WORD_1
	v_pk_mul_f32 v[110:111], v[110:111], s[90:91] op_sel_hi:[1, 0]
	v_pk_mul_f32 v[112:113], v[112:113], s[90:91] op_sel_hi:[1, 0]
	v_pk_fma_f32 v[124:125], v[104:105], v[228:229], v[110:111]
	v_pk_fma_f32 v[122:123], v[102:103], v[226:227], v[112:113]
	v_cvt_f32_f16_e32 v102, v221
	v_cvt_f32_f16_sdwa v103, v221 dst_sel:DWORD dst_unused:UNUSED_PAD src0_sel:WORD_1
	v_cvt_f32_f16_e32 v104, v220
	v_cvt_f32_f16_sdwa v105, v220 dst_sel:DWORD dst_unused:UNUSED_PAD src0_sel:WORD_1
	v_pk_mul_f32 v[102:103], v[102:103], s[90:91] op_sel_hi:[1, 0]
	v_pk_mul_f32 v[104:105], v[104:105], s[90:91] op_sel_hi:[1, 0]
	v_pk_fma_f32 v[120:121], v[96:97], v[228:229], v[102:103]
	v_pk_fma_f32 v[118:119], v[94:95], v[226:227], v[104:105]
	v_cvt_f32_f16_e32 v94, v219
	v_cvt_f32_f16_sdwa v95, v219 dst_sel:DWORD dst_unused:UNUSED_PAD src0_sel:WORD_1
	v_cvt_f32_f16_e32 v96, v218
	v_cvt_f32_f16_sdwa v97, v218 dst_sel:DWORD dst_unused:UNUSED_PAD src0_sel:WORD_1
	v_pk_mul_f32 v[94:95], v[94:95], s[90:91] op_sel_hi:[1, 0]
	v_pk_mul_f32 v[96:97], v[96:97], s[90:91] op_sel_hi:[1, 0]
	v_pk_fma_f32 v[116:117], v[76:77], v[228:229], v[94:95]
	v_pk_fma_f32 v[114:115], v[74:75], v[226:227], v[96:97]
	v_cvt_f32_f16_e32 v94, v216
	v_cvt_f32_f16_sdwa v95, v216 dst_sel:DWORD dst_unused:UNUSED_PAD src0_sel:WORD_1
	v_cvt_f32_f16_e32 v96, v217
	v_cvt_f32_f16_sdwa v97, v217 dst_sel:DWORD dst_unused:UNUSED_PAD src0_sel:WORD_1
	v_pk_mul_f32 v[76:77], v[234:235], 0.5 op_sel_hi:[1, 0]
	v_pk_mul_f32 v[74:75], v[232:233], 0.5 op_sel_hi:[1, 0]
	v_pk_mul_f32 v[102:103], v[108:109], v[76:77]
	v_pk_mul_f32 v[104:105], v[106:107], v[74:75]
	v_pk_fma_f32 v[112:113], v[96:97], s[90:91], v[102:103] op_sel_hi:[1, 0, 1]
	v_pk_fma_f32 v[110:111], v[94:95], s[90:91], v[104:105] op_sel_hi:[1, 0, 1]
	v_cvt_f32_f16_e32 v94, v214
	v_cvt_f32_f16_sdwa v95, v214 dst_sel:DWORD dst_unused:UNUSED_PAD src0_sel:WORD_1
	v_cvt_f32_f16_e32 v96, v215
	v_cvt_f32_f16_sdwa v97, v215 dst_sel:DWORD dst_unused:UNUSED_PAD src0_sel:WORD_1
	v_pk_mul_f32 v[100:101], v[100:101], v[76:77]
	v_pk_mul_f32 v[98:99], v[98:99], v[74:75]
	v_pk_mul_f32 v[92:93], v[92:93], v[76:77]
	v_pk_fma_f32 v[108:109], v[96:97], s[90:91], v[100:101] op_sel_hi:[1, 0, 1]
	v_pk_fma_f32 v[106:107], v[94:95], s[90:91], v[98:99] op_sel_hi:[1, 0, 1]
	v_cvt_f32_f16_e32 v94, v212
	v_cvt_f32_f16_sdwa v95, v212 dst_sel:DWORD dst_unused:UNUSED_PAD src0_sel:WORD_1
	v_cvt_f32_f16_e32 v96, v213
	v_cvt_f32_f16_sdwa v97, v213 dst_sel:DWORD dst_unused:UNUSED_PAD src0_sel:WORD_1
	v_pk_mul_f32 v[90:91], v[90:91], v[74:75]
	v_pk_mul_f32 v[80:81], v[80:81], v[76:77]
	v_pk_fma_f32 v[102:103], v[94:95], s[90:91], v[90:91] op_sel_hi:[1, 0, 1]
	v_pk_fma_f32 v[104:105], v[96:97], s[90:91], v[92:93] op_sel_hi:[1, 0, 1]
	v_cvt_f32_f16_e32 v90, v210
	v_cvt_f32_f16_sdwa v91, v210 dst_sel:DWORD dst_unused:UNUSED_PAD src0_sel:WORD_1
	v_cvt_f32_f16_e32 v92, v211
	v_cvt_f32_f16_sdwa v93, v211 dst_sel:DWORD dst_unused:UNUSED_PAD src0_sel:WORD_1
	v_pk_mul_f32 v[78:79], v[78:79], v[74:75]
	v_pk_mul_f32 v[72:73], v[72:73], v[76:77]
	v_pk_fma_f32 v[98:99], v[90:91], s[90:91], v[78:79] op_sel_hi:[1, 0, 1]
	v_pk_fma_f32 v[100:101], v[92:93], s[90:91], v[80:81] op_sel_hi:[1, 0, 1]
	v_cvt_f32_f16_e32 v78, v208
	v_cvt_f32_f16_sdwa v79, v208 dst_sel:DWORD dst_unused:UNUSED_PAD src0_sel:WORD_1
	v_cvt_f32_f16_e32 v80, v209
	v_cvt_f32_f16_sdwa v81, v209 dst_sel:DWORD dst_unused:UNUSED_PAD src0_sel:WORD_1
	v_pk_mul_f32 v[70:71], v[70:71], v[74:75]
	v_pk_mul_f32 v[64:65], v[64:65], v[76:77]
	v_pk_fma_f32 v[94:95], v[78:79], s[90:91], v[70:71] op_sel_hi:[1, 0, 1]
	v_pk_fma_f32 v[96:97], v[80:81], s[90:91], v[72:73] op_sel_hi:[1, 0, 1]
	v_cvt_f32_f16_e32 v70, v206
	v_cvt_f32_f16_sdwa v71, v206 dst_sel:DWORD dst_unused:UNUSED_PAD src0_sel:WORD_1
	v_cvt_f32_f16_e32 v72, v207
	v_cvt_f32_f16_sdwa v73, v207 dst_sel:DWORD dst_unused:UNUSED_PAD src0_sel:WORD_1
	v_pk_mul_f32 v[62:63], v[62:63], v[74:75]
	v_pk_mul_f32 v[60:61], v[60:61], v[76:77]
	v_pk_fma_f32 v[90:91], v[70:71], s[90:91], v[62:63] op_sel_hi:[1, 0, 1]
	v_pk_fma_f32 v[92:93], v[72:73], s[90:91], v[64:65] op_sel_hi:[1, 0, 1]
	v_cvt_f32_f16_e32 v62, v204
	v_cvt_f32_f16_sdwa v63, v204 dst_sel:DWORD dst_unused:UNUSED_PAD src0_sel:WORD_1
	v_cvt_f32_f16_e32 v64, v205
	v_cvt_f32_f16_sdwa v65, v205 dst_sel:DWORD dst_unused:UNUSED_PAD src0_sel:WORD_1
	v_pk_mul_f32 v[58:59], v[58:59], v[74:75]
	v_pk_mul_f32 v[52:53], v[52:53], v[76:77]
	v_pk_fma_f32 v[78:79], v[62:63], s[90:91], v[58:59] op_sel_hi:[1, 0, 1]
	v_pk_fma_f32 v[80:81], v[64:65], s[90:91], v[60:61] op_sel_hi:[1, 0, 1]
	v_cvt_f32_f16_e32 v58, v202
	v_cvt_f32_f16_sdwa v59, v202 dst_sel:DWORD dst_unused:UNUSED_PAD src0_sel:WORD_1
	v_cvt_f32_f16_e32 v60, v203
	v_cvt_f32_f16_sdwa v61, v203 dst_sel:DWORD dst_unused:UNUSED_PAD src0_sel:WORD_1
	v_pk_mul_f32 v[50:51], v[50:51], v[74:75]
	v_pk_fma_f32 v[76:77], v[60:61], s[90:91], v[52:53] op_sel_hi:[1, 0, 1]
	v_pk_fma_f32 v[74:75], v[58:59], s[90:91], v[50:51] op_sel_hi:[1, 0, 1]
	s_nop 0
	v_pk_mul_f32 v[204:205], v[238:239], 0.5 op_sel_hi:[1, 0]
	v_pk_mul_f32 v[202:203], v[236:237], 0.5 op_sel_hi:[1, 0]
	v_cvt_f32_f16_e32 v50, v200
	v_cvt_f32_f16_sdwa v51, v200 dst_sel:DWORD dst_unused:UNUSED_PAD src0_sel:WORD_1
	v_cvt_f32_f16_e32 v52, v201
	v_cvt_f32_f16_sdwa v53, v201 dst_sel:DWORD dst_unused:UNUSED_PAD src0_sel:WORD_1
	v_pk_mul_f32 v[58:59], v[68:69], v[204:205]
	v_pk_mul_f32 v[60:61], v[66:67], v[202:203]
	v_pk_mul_f32 v[56:57], v[56:57], v[204:205]
	v_pk_fma_f32 v[72:73], v[52:53], s[90:91], v[58:59] op_sel_hi:[1, 0, 1]
	v_pk_fma_f32 v[70:71], v[50:51], s[90:91], v[60:61] op_sel_hi:[1, 0, 1]
	v_cvt_f32_f16_e32 v50, v176
	v_cvt_f32_f16_sdwa v51, v176 dst_sel:DWORD dst_unused:UNUSED_PAD src0_sel:WORD_1
	v_cvt_f32_f16_e32 v52, v177
	v_cvt_f32_f16_sdwa v53, v177 dst_sel:DWORD dst_unused:UNUSED_PAD src0_sel:WORD_1
	v_pk_mul_f32 v[54:55], v[54:55], v[202:203]
	v_pk_mul_f32 v[48:49], v[48:49], v[204:205]
	v_pk_fma_f32 v[66:67], v[50:51], s[90:91], v[54:55] op_sel_hi:[1, 0, 1]
	v_pk_fma_f32 v[68:69], v[52:53], s[90:91], v[56:57] op_sel_hi:[1, 0, 1]
	v_cvt_f32_f16_e32 v50, v174
	v_cvt_f32_f16_sdwa v51, v174 dst_sel:DWORD dst_unused:UNUSED_PAD src0_sel:WORD_1
	v_cvt_f32_f16_e32 v52, v175
	v_cvt_f32_f16_sdwa v53, v175 dst_sel:DWORD dst_unused:UNUSED_PAD src0_sel:WORD_1
	v_pk_mul_f32 v[46:47], v[46:47], v[202:203]
	v_pk_mul_f32 v[44:45], v[44:45], v[204:205]
	v_pk_fma_f32 v[62:63], v[50:51], s[90:91], v[46:47] op_sel_hi:[1, 0, 1]
	v_pk_fma_f32 v[64:65], v[52:53], s[90:91], v[48:49] op_sel_hi:[1, 0, 1]
	v_cvt_f32_f16_e32 v46, v172
	v_cvt_f32_f16_sdwa v47, v172 dst_sel:DWORD dst_unused:UNUSED_PAD src0_sel:WORD_1
	v_cvt_f32_f16_e32 v48, v173
	v_cvt_f32_f16_sdwa v49, v173 dst_sel:DWORD dst_unused:UNUSED_PAD src0_sel:WORD_1
	v_pk_mul_f32 v[42:43], v[42:43], v[202:203]
	v_pk_mul_f32 v[40:41], v[40:41], v[204:205]
	v_pk_fma_f32 v[58:59], v[46:47], s[90:91], v[42:43] op_sel_hi:[1, 0, 1]
	v_pk_fma_f32 v[60:61], v[48:49], s[90:91], v[44:45] op_sel_hi:[1, 0, 1]
	v_cvt_f32_f16_e32 v42, v170
	v_cvt_f32_f16_sdwa v43, v170 dst_sel:DWORD dst_unused:UNUSED_PAD src0_sel:WORD_1
	v_cvt_f32_f16_e32 v44, v171
	v_cvt_f32_f16_sdwa v45, v171 dst_sel:DWORD dst_unused:UNUSED_PAD src0_sel:WORD_1
	v_pk_mul_f32 v[38:39], v[38:39], v[202:203]
	v_pk_mul_f32 v[36:37], v[36:37], v[204:205]
	v_pk_fma_f32 v[54:55], v[42:43], s[90:91], v[38:39] op_sel_hi:[1, 0, 1]
	v_pk_fma_f32 v[56:57], v[44:45], s[90:91], v[40:41] op_sel_hi:[1, 0, 1]
	v_cvt_f32_f16_e32 v38, v168
	v_cvt_f32_f16_sdwa v39, v168 dst_sel:DWORD dst_unused:UNUSED_PAD src0_sel:WORD_1
	v_cvt_f32_f16_e32 v40, v169
	v_cvt_f32_f16_sdwa v41, v169 dst_sel:DWORD dst_unused:UNUSED_PAD src0_sel:WORD_1
	v_pk_mul_f32 v[34:35], v[34:35], v[202:203]
	v_pk_mul_f32 v[32:33], v[32:33], v[204:205]
	v_pk_fma_f32 v[50:51], v[38:39], s[90:91], v[34:35] op_sel_hi:[1, 0, 1]
	v_pk_fma_f32 v[52:53], v[40:41], s[90:91], v[36:37] op_sel_hi:[1, 0, 1]
	v_cvt_f32_f16_e32 v34, v166
	v_cvt_f32_f16_sdwa v35, v166 dst_sel:DWORD dst_unused:UNUSED_PAD src0_sel:WORD_1
	v_cvt_f32_f16_e32 v36, v167
	v_cvt_f32_f16_sdwa v37, v167 dst_sel:DWORD dst_unused:UNUSED_PAD src0_sel:WORD_1
	v_pk_mul_f32 v[30:31], v[30:31], v[202:203]
	v_pk_mul_f32 v[24:25], v[24:25], v[204:205]
	v_pk_fma_f32 v[46:47], v[34:35], s[90:91], v[30:31] op_sel_hi:[1, 0, 1]
	v_pk_fma_f32 v[48:49], v[36:37], s[90:91], v[32:33] op_sel_hi:[1, 0, 1]
	v_cvt_f32_f16_e32 v30, v164
	v_cvt_f32_f16_sdwa v31, v164 dst_sel:DWORD dst_unused:UNUSED_PAD src0_sel:WORD_1
	v_cvt_f32_f16_e32 v32, v165
	v_cvt_f32_f16_sdwa v33, v165 dst_sel:DWORD dst_unused:UNUSED_PAD src0_sel:WORD_1
	v_pk_mul_f32 v[22:23], v[22:23], v[202:203]
	v_pk_fma_f32 v[44:45], v[32:33], s[90:91], v[24:25] op_sel_hi:[1, 0, 1]
	v_pk_fma_f32 v[42:43], v[30:31], s[90:91], v[22:23] op_sel_hi:[1, 0, 1]
	s_nop 0
	v_mov_b32_e32 v168, v110
	v_mov_b32_e32 v169, v113
	v_add_f32_e32 v170, v72, v73
	v_pk_mul_f32 v[166:167], v[242:243], 0.5 op_sel_hi:[1, 0]
	v_pk_mul_f32 v[164:165], v[240:241], 0.5 op_sel_hi:[1, 0]
	v_cvt_f32_f16_e32 v22, v160
	v_cvt_f32_f16_sdwa v23, v160 dst_sel:DWORD dst_unused:UNUSED_PAD src0_sel:WORD_1
	v_cvt_f32_f16_e32 v24, v161
	v_cvt_f32_f16_sdwa v25, v161 dst_sel:DWORD dst_unused:UNUSED_PAD src0_sel:WORD_1
	v_pk_mul_f32 v[30:31], v[88:89], v[166:167]
	v_pk_mul_f32 v[32:33], v[86:87], v[164:165]
	v_pk_mul_f32 v[34:35], v[82:83], v[164:165]
	v_pk_fma_f32 v[40:41], v[24:25], s[90:91], v[30:31] op_sel_hi:[1, 0, 1]
	v_pk_fma_f32 v[38:39], v[22:23], s[90:91], v[32:33] op_sel_hi:[1, 0, 1]
	v_cvt_f32_f16_e32 v22, v158
	v_cvt_f32_f16_sdwa v23, v158 dst_sel:DWORD dst_unused:UNUSED_PAD src0_sel:WORD_1
	v_cvt_f32_f16_e32 v24, v159
	v_cvt_f32_f16_sdwa v25, v159 dst_sel:DWORD dst_unused:UNUSED_PAD src0_sel:WORD_1
	v_pk_mul_f32 v[30:31], v[84:85], v[166:167]
	v_pk_mul_f32 v[28:29], v[28:29], v[166:167]
	v_pk_mul_f32 v[26:27], v[26:27], v[164:165]
	v_pk_fma_f32 v[32:33], v[24:25], s[90:91], v[30:31] op_sel_hi:[1, 0, 1]
	v_pk_fma_f32 v[30:31], v[22:23], s[90:91], v[34:35] op_sel_hi:[1, 0, 1]
	v_cvt_f32_f16_e32 v22, v156
	v_cvt_f32_f16_sdwa v23, v156 dst_sel:DWORD dst_unused:UNUSED_PAD src0_sel:WORD_1
	v_cvt_f32_f16_e32 v24, v157
	v_cvt_f32_f16_sdwa v25, v157 dst_sel:DWORD dst_unused:UNUSED_PAD src0_sel:WORD_1
	v_pk_mul_f32 v[20:21], v[20:21], v[166:167]
	v_pk_fma_f32 v[34:35], v[22:23], s[90:91], v[26:27] op_sel_hi:[1, 0, 1]
	v_cvt_f32_f16_e32 v22, v154
	v_pk_fma_f32 v[36:37], v[24:25], s[90:91], v[28:29] op_sel_hi:[1, 0, 1]
	v_cvt_f32_f16_sdwa v23, v154 dst_sel:DWORD dst_unused:UNUSED_PAD src0_sel:WORD_1
	v_cvt_f32_f16_e32 v24, v155
	v_cvt_f32_f16_sdwa v25, v155 dst_sel:DWORD dst_unused:UNUSED_PAD src0_sel:WORD_1
	v_pk_mul_f32 v[18:19], v[18:19], v[164:165]
	v_pk_mul_f32 v[16:17], v[16:17], v[166:167]
	v_pk_fma_f32 v[26:27], v[22:23], s[90:91], v[18:19] op_sel_hi:[1, 0, 1]
	v_pk_fma_f32 v[28:29], v[24:25], s[90:91], v[20:21] op_sel_hi:[1, 0, 1]
	v_cvt_f32_f16_e32 v18, v152
	v_cvt_f32_f16_sdwa v19, v152 dst_sel:DWORD dst_unused:UNUSED_PAD src0_sel:WORD_1
	v_cvt_f32_f16_e32 v20, v153
	v_cvt_f32_f16_sdwa v21, v153 dst_sel:DWORD dst_unused:UNUSED_PAD src0_sel:WORD_1
	v_pk_mul_f32 v[14:15], v[14:15], v[164:165]
	v_pk_mul_f32 v[12:13], v[12:13], v[166:167]
	v_pk_fma_f32 v[22:23], v[18:19], s[90:91], v[14:15] op_sel_hi:[1, 0, 1]
	v_pk_fma_f32 v[24:25], v[20:21], s[90:91], v[16:17] op_sel_hi:[1, 0, 1]
	v_cvt_f32_f16_e32 v14, v150
	v_cvt_f32_f16_sdwa v15, v150 dst_sel:DWORD dst_unused:UNUSED_PAD src0_sel:WORD_1
	v_cvt_f32_f16_e32 v16, v151
	v_cvt_f32_f16_sdwa v17, v151 dst_sel:DWORD dst_unused:UNUSED_PAD src0_sel:WORD_1
	v_pk_mul_f32 v[10:11], v[10:11], v[164:165]
	v_pk_mul_f32 v[8:9], v[8:9], v[166:167]
	v_pk_fma_f32 v[18:19], v[14:15], s[90:91], v[10:11] op_sel_hi:[1, 0, 1]
	v_pk_fma_f32 v[20:21], v[16:17], s[90:91], v[12:13] op_sel_hi:[1, 0, 1]
	v_cvt_f32_f16_e32 v10, v148
	v_cvt_f32_f16_sdwa v11, v148 dst_sel:DWORD dst_unused:UNUSED_PAD src0_sel:WORD_1
	v_cvt_f32_f16_e32 v12, v149
	v_cvt_f32_f16_sdwa v13, v149 dst_sel:DWORD dst_unused:UNUSED_PAD src0_sel:WORD_1
	v_pk_mul_f32 v[6:7], v[6:7], v[164:165]
	v_pk_mul_f32 v[4:5], v[4:5], v[166:167]
	v_pk_fma_f32 v[14:15], v[10:11], s[90:91], v[6:7] op_sel_hi:[1, 0, 1]
	v_pk_fma_f32 v[16:17], v[12:13], s[90:91], v[8:9] op_sel_hi:[1, 0, 1]
	v_cvt_f32_f16_e32 v6, v146
	v_cvt_f32_f16_sdwa v7, v146 dst_sel:DWORD dst_unused:UNUSED_PAD src0_sel:WORD_1
	v_cvt_f32_f16_e32 v8, v147
	v_cvt_f32_f16_sdwa v9, v147 dst_sel:DWORD dst_unused:UNUSED_PAD src0_sel:WORD_1
	v_pk_mul_f32 v[2:3], v[2:3], v[164:165]
	v_pk_fma_f32 v[4:5], v[8:9], s[90:91], v[4:5] op_sel_hi:[1, 0, 1]
	v_pk_fma_f32 v[2:3], v[6:7], s[90:91], v[2:3] op_sel_hi:[1, 0, 1]
	s_nop 0
	v_lshl_add_u64 v[6:7], s[8:9], 0, v[162:163]
	v_lshl_add_u64 v[10:11], s[6:7], 0, v[162:163]
	global_load_dwordx4 v[158:161], v[6:7], off
	global_load_dwordx4 v[162:165], v[10:11], off
	global_load_dwordx4 v[146:149], v[6:7], off offset:64
	global_load_dwordx4 v[150:153], v[10:11], off offset:64
	global_load_dwordx4 v[82:85], v[6:7], off offset:512
	global_load_dwordx4 v[86:89], v[10:11], off offset:512
	s_nop 0
	global_load_dwordx4 v[6:9], v[6:7], off offset:576
	s_nop 0
	global_load_dwordx4 v[10:13], v[10:11], off offset:576
	v_and_b32_e32 v155, 64, v249
	v_xor_b32_e32 v154, 16, v249
	v_add_u32_e32 v155, 64, v155
	v_cmp_lt_i32_e32 vcc, v154, v155
	v_xor_b32_e32 v156, 32, v249
	v_mov_b32_e32 v157, v144
	v_cndmask_b32_e32 v154, v249, v154, vcc
	v_cmp_lt_i32_e32 vcc, v156, v155
	v_mov_b32_e32 v166, v142
	v_mov_b32_e32 v167, v145
	v_cndmask_b32_e32 v155, v249, v156, vcc
	v_mov_b32_e32 v156, v143
	v_pk_add_f32 v[156:157], v[156:157], v[166:167]
	v_mov_b32_e32 v166, v111
	v_mov_b32_e32 v167, v112
	v_pk_add_f32 v[166:167], v[166:167], v[168:169]
	v_add_f32_e32 v156, v156, v157
	v_pk_add_f32 v[166:167], v[166:167], v[166:167] op_sel:[0,1] op_sel_hi:[1,0]
	v_add_f32_e32 v156, 0, v156
	v_add_f32_e32 v168, v70, v71
	v_mov_b32_e32 v157, v38
	v_mov_b32_e32 v167, v39
	v_mov_b32_e32 v169, v40
	v_mov_b32_e32 v171, v41
	v_pk_add_f32 v[156:157], v[156:157], v[166:167]
	v_pk_add_f32 v[166:167], v[168:169], v[170:171]
	v_lshlrev_b32_e32 v154, 2, v154
	v_pk_add_f32 v[156:157], v[156:157], v[166:167]
	v_lshlrev_b32_e32 v155, 2, v155
	v_add_f32_e32 v156, v156, v157
	v_mov_b32_e32 v157, v156
	s_nop 1
	v_permlane16_swap_b32_e32 v157, v156
	v_cmp_gt_u32_e32 vcc, 16, v0
	s_waitcnt lgkmcnt(0)
	v_add_f32_e32 v156, v156, v157
	v_mov_b32_e32 v157, v156
	s_nop 1
	v_permlane32_swap_b32_e32 v157, v156
	s_waitcnt lgkmcnt(0)
	v_add_f32_e32 v156, v156, v157
	v_fmamk_f32 v166, v156, 0xbc800000, v145
	v_fmamk_f32 v168, v156, 0xbc800000, v143
	v_fmamk_f32 v157, v156, 0xbc800000, v144
	v_fmamk_f32 v167, v156, 0xbc800000, v142
	v_mul_f32_e32 v168, v168, v168
	v_mul_f32_e32 v166, v166, v166
	v_fmac_f32_e32 v168, v167, v167
	v_fmac_f32_e32 v166, v157, v157
	v_fmamk_f32 v167, v156, 0xbc800000, v113
	v_fmamk_f32 v169, v156, 0xbc800000, v111
	v_add_f32_e32 v157, v168, v166
	v_fmamk_f32 v166, v156, 0xbc800000, v112
	v_fmamk_f32 v168, v156, 0xbc800000, v110
	v_mul_f32_e32 v169, v169, v169
	v_mul_f32_e32 v167, v167, v167
	v_fmac_f32_e32 v169, v168, v168
	v_fmac_f32_e32 v167, v166, v166
	v_add_f32_e32 v166, v169, v167
	v_fmamk_f32 v167, v156, 0xbc800000, v73
	v_fmamk_f32 v169, v156, 0xbc800000, v71
	v_add_f32_e32 v157, v157, v166
	v_fmamk_f32 v166, v156, 0xbc800000, v72
	v_fmamk_f32 v168, v156, 0xbc800000, v70
	v_mul_f32_e32 v169, v169, v169
	v_mul_f32_e32 v167, v167, v167
	v_fmac_f32_e32 v169, v168, v168
	v_fmac_f32_e32 v167, v166, v166
	v_add_f32_e32 v166, v169, v167
	v_fmamk_f32 v167, v156, 0xbc800000, v41
	v_fmamk_f32 v169, v156, 0xbc800000, v39
	v_add_f32_e32 v157, v166, v157
	v_fmamk_f32 v166, v156, 0xbc800000, v40
	v_fmamk_f32 v168, v156, 0xbc800000, v38
	v_mul_f32_e32 v169, v169, v169
	v_mul_f32_e32 v167, v167, v167
	v_fmac_f32_e32 v169, v168, v168
	v_fmac_f32_e32 v167, v166, v166
	v_add_f32_e32 v166, v169, v167
	v_add_f32_e32 v157, v166, v157
	v_mov_b32_e32 v166, v157
	s_nop 1
	v_permlane16_swap_b32_e32 v166, v157
	s_waitcnt lgkmcnt(0)
	v_add_f32_e32 v157, v157, v166
	v_mov_b32_e32 v166, v157
	s_nop 1
	v_permlane32_swap_b32_e32 v166, v157
	s_and_saveexec_b64 s[6:7], vcc
	s_cbranch_execz .LBB0_335
	s_lshl_b32 s8, s52, 11
	s_add_i32 s8, s2, s8
	v_mul_f32_e32 v156, 0x3c800000, v156
	v_lshl_add_u32 v167, v0, 5, s8
	s_waitcnt lgkmcnt(0)
	v_add_f32_e32 v157, v157, v166
	ds_write_b64 v167, v[156:157]

.LBB0_1173:
	v_readlane_b32 s6, v253, 9
	v_readlane_b32 s7, v253, 10
	s_lshl_b64 s[6:7], s[6:7], 2
	s_add_u32 s2, s12, s6
	s_addc_u32 s6, s13, s7
	s_add_u32 s30, s2, 0x100000
	s_addc_u32 s31, s6, 0
	s_lshl_b64 s[6:7], s[66:67], 2
	s_add_u32 s22, s8, s6
	s_addc_u32 s23, s9, s7
	s_add_u32 s6, s10, s6
	s_addc_u32 s7, s11, s7
	v_mbcnt_lo_u32_b32 v0, -1, 0
	v_mbcnt_hi_u32_b32 v0, -1, v0
	s_lshl_b32 s8, s16, 8
	v_ashrrev_i32_e32 v130, 2, v0
	s_or_b32 s8, s8, s43
	v_and_b32_e32 v130, -4, v130
	v_add_u32_e32 v196, s8, v130
	s_lshl_b32 s8, s14, 8
	s_ashr_i32 s9, s8, 31
	s_ashr_i32 s2, s14, 3
	s_lshl_b64 s[18:19], s[8:9], 11
	s_add_u32 s20, s12, s18
	v_and_or_b32 v212, v0, 15, s87
	s_addc_u32 s21, s13, s19
	v_ashrrev_i32_e32 v197, 31, v196
	v_add_u32_e32 v204, 0x80, v212
	v_lshl_add_u64 v[130:131], v[196:197], 1, s[20:21]
	s_mov_b64 s[20:21], 0x5200000
	v_ashrrev_i32_e32 v205, 31, v204
	v_ashrrev_i32_e32 v213, 31, v212
	v_add_u32_e32 v202, 0x90, v212
	s_mul_hi_i32 s11, s2, 0x2400
	s_mul_i32 s10, s2, 0x2400
	v_lshl_add_u64 v[130:131], v[130:131], 0, s[20:21]
	v_lshlrev_b64 v[132:133], 11, v[204:205]
	v_lshlrev_b64 v[134:135], 11, v[212:213]
	v_or_b32_e32 v210, 16, v212
	v_ashrrev_i32_e32 v203, 31, v202
	v_add_u32_e32 v200, 0xa0, v212
	v_lshl_add_u64 v[194:195], v[130:131], 0, v[134:135]
	v_ashrrev_i32_e32 v211, 31, v210
	v_or_b32_e32 v208, 32, v212
	v_or_b32_e32 v206, 48, v212
	v_lshl_add_u64 v[186:187], v[130:131], 0, v[132:133]
	v_lshlrev_b64 v[132:133], 11, v[202:203]
	v_ashrrev_i32_e32 v201, 31, v200
	v_add_u32_e32 v198, 0xb0, v212
	s_lshl_b64 s[20:21], s[10:11], 2
	global_load_dwordx2 v[146:147], v[194:195], off
	v_lshlrev_b64 v[134:135], 11, v[210:211]
	v_ashrrev_i32_e32 v209, 31, v208
	v_ashrrev_i32_e32 v207, 31, v206
	v_lshl_add_u64 v[184:185], v[130:131], 0, v[132:133]
	v_lshlrev_b64 v[132:133], 11, v[200:201]
	v_ashrrev_i32_e32 v199, 31, v198
	s_add_u32 s10, s30, s20
	v_lshl_add_u64 v[192:193], v[130:131], 0, v[134:135]
	v_lshlrev_b64 v[134:135], 11, v[208:209]
	v_lshlrev_b64 v[138:139], 11, v[206:207]
	v_lshl_add_u64 v[182:183], v[130:131], 0, v[132:133]
	v_lshlrev_b64 v[132:133], 11, v[198:199]
	s_addc_u32 s11, s31, s21
	v_lshlrev_b64 v[158:159], 2, v[196:197]
	v_lshl_add_u64 v[190:191], v[130:131], 0, v[134:135]
	v_lshl_add_u64 v[188:189], v[130:131], 0, v[138:139]
	v_lshl_add_u64 v[180:181], v[130:131], 0, v[132:133]
	v_lshl_add_u64 v[130:131], s[10:11], 0, v[158:159]
	s_mov_b64 s[10:11], 0x5000
	s_movk_i32 s2, 0x5000
	v_lshl_add_u64 v[214:215], v[130:131], 0, s[10:11]
	v_add_co_u32_e32 v130, vcc, s2, v130
	global_load_dwordx2 v[136:137], v[192:193], off
	global_load_dwordx2 v[134:135], v[190:191], off
	v_addc_co_u32_e32 v131, vcc, 0, v131, vcc
	global_load_dwordx2 v[242:243], v[188:189], off
	global_load_dwordx2 v[240:241], v[186:187], off
	global_load_dwordx2 v[238:239], v[184:185], off
	global_load_dwordx2 v[236:237], v[182:183], off
	global_load_dwordx2 v[234:235], v[180:181], off
	global_load_dwordx2 v[232:233], v[194:195], off offset:32
	global_load_dwordx2 v[230:231], v[192:193], off offset:32
	global_load_dwordx2 v[228:229], v[190:191], off offset:32
	global_load_dwordx2 v[226:227], v[188:189], off offset:32
	global_load_dwordx2 v[224:225], v[186:187], off offset:32
	global_load_dwordx2 v[222:223], v[184:185], off offset:32
	global_load_dwordx2 v[220:221], v[182:183], off offset:32
	global_load_dwordx2 v[218:219], v[180:181], off offset:32
	global_load_dwordx2 v[216:217], v[194:195], off offset:256
	global_load_dwordx2 v[176:177], v[192:193], off offset:256
	global_load_dwordx2 v[174:175], v[190:191], off offset:256
	global_load_dwordx2 v[172:173], v[188:189], off offset:256
	global_load_dwordx2 v[170:171], v[186:187], off offset:256
	global_load_dwordx2 v[168:169], v[184:185], off offset:256
	global_load_dwordx2 v[166:167], v[182:183], off offset:256
	global_load_dwordx2 v[164:165], v[180:181], off offset:256
	global_load_dwordx2 v[162:163], v[194:195], off offset:288
	global_load_dwordx2 v[160:161], v[192:193], off offset:288
	global_load_dwordx2 v[156:157], v[190:191], off offset:288
	global_load_dwordx2 v[154:155], v[188:189], off offset:288
	global_load_dwordx2 v[144:145], v[186:187], off offset:288
	global_load_dwordx2 v[142:143], v[184:185], off offset:288
	global_load_dwordx2 v[140:141], v[182:183], off offset:288
	global_load_dwordx2 v[138:139], v[180:181], off offset:288
	s_lshl_b32 s2, s92, 3
	global_load_dwordx4 v[130:133], v[130:131], off
	s_add_i32 s2, s2, 0
	s_waitcnt vmcnt(0)
	s_barrier
	v_cvt_f32_f16_e32 v148, v147
	v_cvt_f32_f16_sdwa v149, v147 dst_sel:DWORD dst_unused:UNUSED_PAD src0_sel:WORD_1
	v_cvt_f32_f16_e32 v150, v146
	v_cvt_f32_f16_sdwa v151, v146 dst_sel:DWORD dst_unused:UNUSED_PAD src0_sel:WORD_1
	v_pk_mul_f32 v[148:149], v[148:149], s[90:91] op_sel_hi:[1,0]
	v_pk_mul_f32 v[146:147], v[150:151], s[90:91] op_sel_hi:[1,0]
	v_pk_fma_f32 v[152:153], v[124:125], v[132:133], v[148:149]
	v_pk_fma_f32 v[150:151], v[122:123], v[130:131], v[146:147]
	v_cvt_f32_f16_e32 v122, v137
	v_cvt_f32_f16_sdwa v123, v137 dst_sel:DWORD dst_unused:UNUSED_PAD src0_sel:WORD_1
	v_cvt_f32_f16_e32 v124, v136
	v_cvt_f32_f16_sdwa v125, v136 dst_sel:DWORD dst_unused:UNUSED_PAD src0_sel:WORD_1
	v_pk_mul_f32 v[122:123], v[122:123], s[90:91] op_sel_hi:[1,0]
	v_pk_mul_f32 v[124:125], v[124:125], s[90:91] op_sel_hi:[1,0]
	v_pk_fma_f32 v[148:149], v[120:121], v[132:133], v[122:123]
	v_pk_fma_f32 v[146:147], v[118:119], v[130:131], v[124:125]
	v_cvt_f32_f16_e32 v118, v135
	v_cvt_f32_f16_sdwa v119, v135 dst_sel:DWORD dst_unused:UNUSED_PAD src0_sel:WORD_1
	v_cvt_f32_f16_e32 v120, v134
	v_cvt_f32_f16_sdwa v121, v134 dst_sel:DWORD dst_unused:UNUSED_PAD src0_sel:WORD_1
	v_pk_mul_f32 v[118:119], v[118:119], s[90:91] op_sel_hi:[1,0]
	v_pk_mul_f32 v[120:121], v[120:121], s[90:91] op_sel_hi:[1,0]
	v_pk_fma_f32 v[136:137], v[116:117], v[132:133], v[118:119]
	v_pk_fma_f32 v[134:135], v[114:115], v[130:131], v[120:121]
	v_cvt_f32_f16_e32 v114, v243
	v_cvt_f32_f16_sdwa v115, v243 dst_sel:DWORD dst_unused:UNUSED_PAD src0_sel:WORD_1
	v_cvt_f32_f16_e32 v116, v242
	v_cvt_f32_f16_sdwa v117, v242 dst_sel:DWORD dst_unused:UNUSED_PAD src0_sel:WORD_1
	v_pk_mul_f32 v[114:115], v[114:115], s[90:91] op_sel_hi:[1,0]
	v_pk_mul_f32 v[116:117], v[116:117], s[90:91] op_sel_hi:[1,0]
	v_pk_fma_f32 v[120:121], v[112:113], v[132:133], v[114:115]
	v_pk_fma_f32 v[118:119], v[110:111], v[130:131], v[116:117]
	v_cvt_f32_f16_e32 v110, v241
	v_cvt_f32_f16_sdwa v111, v241 dst_sel:DWORD dst_unused:UNUSED_PAD src0_sel:WORD_1
	v_cvt_f32_f16_e32 v112, v240
	v_cvt_f32_f16_sdwa v113, v240 dst_sel:DWORD dst_unused:UNUSED_PAD src0_sel:WORD_1
	v_pk_mul_f32 v[110:111], v[110:111], s[90:91] op_sel_hi:[1,0]
	v_pk_mul_f32 v[112:113], v[112:113], s[90:91] op_sel_hi:[1,0]
	v_pk_fma_f32 v[124:125], v[108:109], v[132:133], v[110:111]
	v_pk_fma_f32 v[122:123], v[106:107], v[130:131], v[112:113]
	v_cvt_f32_f16_e32 v106, v239
	v_cvt_f32_f16_sdwa v107, v239 dst_sel:DWORD dst_unused:UNUSED_PAD src0_sel:WORD_1
	v_cvt_f32_f16_e32 v108, v238
	v_cvt_f32_f16_sdwa v109, v238 dst_sel:DWORD dst_unused:UNUSED_PAD src0_sel:WORD_1
	v_pk_mul_f32 v[106:107], v[106:107], s[90:91] op_sel_hi:[1,0]
	v_pk_mul_f32 v[108:109], v[108:109], s[90:91] op_sel_hi:[1,0]
	v_pk_fma_f32 v[116:117], v[100:101], v[132:133], v[106:107]
	v_pk_fma_f32 v[114:115], v[98:99], v[130:131], v[108:109]
	v_cvt_f32_f16_e32 v98, v237
	v_cvt_f32_f16_sdwa v99, v237 dst_sel:DWORD dst_unused:UNUSED_PAD src0_sel:WORD_1
	v_cvt_f32_f16_e32 v100, v236
	v_cvt_f32_f16_sdwa v101, v236 dst_sel:DWORD dst_unused:UNUSED_PAD src0_sel:WORD_1
	v_pk_mul_f32 v[98:99], v[98:99], s[90:91] op_sel_hi:[1,0]
	v_pk_mul_f32 v[100:101], v[100:101], s[90:91] op_sel_hi:[1,0]
	v_pk_fma_f32 v[112:113], v[88:89], v[132:133], v[98:99]
	v_pk_fma_f32 v[110:111], v[86:87], v[130:131], v[100:101]
	v_cvt_f32_f16_e32 v86, v235
	v_cvt_f32_f16_sdwa v87, v235 dst_sel:DWORD dst_unused:UNUSED_PAD src0_sel:WORD_1
	v_cvt_f32_f16_e32 v88, v234
	v_cvt_f32_f16_sdwa v89, v234 dst_sel:DWORD dst_unused:UNUSED_PAD src0_sel:WORD_1
	v_pk_mul_f32 v[86:87], v[86:87], s[90:91] op_sel_hi:[1,0]
	v_pk_mul_f32 v[88:89], v[88:89], s[90:91] op_sel_hi:[1,0]
	v_pk_fma_f32 v[108:109], v[80:81], v[132:133], v[86:87]
	v_pk_fma_f32 v[106:107], v[78:79], v[130:131], v[88:89]
	v_cvt_f32_f16_e32 v78, v233
	global_load_dwordx4 v[130:133], v[214:215], off offset:64
	v_cvt_f32_f16_sdwa v79, v233 dst_sel:DWORD dst_unused:UNUSED_PAD src0_sel:WORD_1
	v_cvt_f32_f16_e32 v80, v232
	v_cvt_f32_f16_sdwa v81, v232 dst_sel:DWORD dst_unused:UNUSED_PAD src0_sel:WORD_1
	s_waitcnt vmcnt(0)
	v_pk_mul_f32 v[86:87], v[104:105], v[132:133]
	v_pk_mul_f32 v[88:89], v[102:103], v[130:131]
	v_pk_fma_f32 v[104:105], v[78:79], s[90:91], v[86:87] op_sel_hi:[1,0,1]
	v_pk_fma_f32 v[102:103], v[80:81], s[90:91], v[88:89] op_sel_hi:[1,0,1]
	v_cvt_f32_f16_e32 v78, v231
	v_cvt_f32_f16_sdwa v79, v231 dst_sel:DWORD dst_unused:UNUSED_PAD src0_sel:WORD_1
	v_cvt_f32_f16_e32 v80, v230
	v_cvt_f32_f16_sdwa v81, v230 dst_sel:DWORD dst_unused:UNUSED_PAD src0_sel:WORD_1
	v_pk_mul_f32 v[86:87], v[96:97], v[132:133]
	v_pk_mul_f32 v[88:89], v[94:95], v[130:131]
	v_pk_fma_f32 v[100:101], v[78:79], s[90:91], v[86:87] op_sel_hi:[1,0,1]
	v_pk_fma_f32 v[98:99], v[80:81], s[90:91], v[88:89] op_sel_hi:[1,0,1]
	v_cvt_f32_f16_e32 v78, v229
	v_cvt_f32_f16_sdwa v79, v229 dst_sel:DWORD dst_unused:UNUSED_PAD src0_sel:WORD_1
	v_cvt_f32_f16_e32 v80, v228
	v_cvt_f32_f16_sdwa v81, v228 dst_sel:DWORD dst_unused:UNUSED_PAD src0_sel:WORD_1
	v_pk_mul_f32 v[86:87], v[92:93], v[132:133]
	v_pk_mul_f32 v[88:89], v[90:91], v[130:131]
	v_pk_fma_f32 v[96:97], v[78:79], s[90:91], v[86:87] op_sel_hi:[1,0,1]
	v_pk_fma_f32 v[94:95], v[80:81], s[90:91], v[88:89] op_sel_hi:[1,0,1]
	v_cvt_f32_f16_e32 v78, v227
	v_cvt_f32_f16_sdwa v79, v227 dst_sel:DWORD dst_unused:UNUSED_PAD src0_sel:WORD_1
	v_cvt_f32_f16_e32 v80, v226
	v_cvt_f32_f16_sdwa v81, v226 dst_sel:DWORD dst_unused:UNUSED_PAD src0_sel:WORD_1
	v_pk_mul_f32 v[84:85], v[84:85], v[132:133]
	v_pk_mul_f32 v[82:83], v[82:83], v[130:131]
	v_pk_fma_f32 v[92:93], v[78:79], s[90:91], v[84:85] op_sel_hi:[1,0,1]
	v_pk_fma_f32 v[90:91], v[80:81], s[90:91], v[82:83] op_sel_hi:[1,0,1]
	v_cvt_f32_f16_e32 v78, v225
	v_cvt_f32_f16_sdwa v79, v225 dst_sel:DWORD dst_unused:UNUSED_PAD src0_sel:WORD_1
	v_cvt_f32_f16_e32 v80, v224
	v_cvt_f32_f16_sdwa v81, v224 dst_sel:DWORD dst_unused:UNUSED_PAD src0_sel:WORD_1
	v_pk_mul_f32 v[76:77], v[76:77], v[132:133]
	v_pk_mul_f32 v[74:75], v[74:75], v[130:131]
	v_pk_fma_f32 v[88:89], v[78:79], s[90:91], v[76:77] op_sel_hi:[1,0,1]
	v_pk_fma_f32 v[86:87], v[80:81], s[90:91], v[74:75] op_sel_hi:[1,0,1]
	v_cvt_f32_f16_e32 v74, v223
	v_cvt_f32_f16_sdwa v75, v223 dst_sel:DWORD dst_unused:UNUSED_PAD src0_sel:WORD_1
	v_cvt_f32_f16_e32 v76, v222
	v_cvt_f32_f16_sdwa v77, v222 dst_sel:DWORD dst_unused:UNUSED_PAD src0_sel:WORD_1
	v_pk_mul_f32 v[64:65], v[64:65], v[132:133]
	v_pk_mul_f32 v[62:63], v[62:63], v[130:131]
	v_pk_fma_f32 v[84:85], v[74:75], s[90:91], v[64:65] op_sel_hi:[1,0,1]
	v_pk_fma_f32 v[82:83], v[76:77], s[90:91], v[62:63] op_sel_hi:[1,0,1]
	v_cvt_f32_f16_e32 v62, v221
	v_cvt_f32_f16_sdwa v63, v221 dst_sel:DWORD dst_unused:UNUSED_PAD src0_sel:WORD_1
	v_cvt_f32_f16_e32 v64, v220
	v_cvt_f32_f16_sdwa v65, v220 dst_sel:DWORD dst_unused:UNUSED_PAD src0_sel:WORD_1
	v_pk_mul_f32 v[60:61], v[60:61], v[132:133]
	v_pk_mul_f32 v[58:59], v[58:59], v[130:131]
	v_pk_fma_f32 v[80:81], v[62:63], s[90:91], v[60:61] op_sel_hi:[1,0,1]
	v_pk_fma_f32 v[78:79], v[64:65], s[90:91], v[58:59] op_sel_hi:[1,0,1]
	v_cvt_f32_f16_e32 v58, v219
	v_cvt_f32_f16_sdwa v59, v219 dst_sel:DWORD dst_unused:UNUSED_PAD src0_sel:WORD_1
	v_cvt_f32_f16_e32 v60, v218
	v_cvt_f32_f16_sdwa v61, v218 dst_sel:DWORD dst_unused:UNUSED_PAD src0_sel:WORD_1
	v_pk_mul_f32 v[56:57], v[56:57], v[132:133]
	v_pk_mul_f32 v[54:55], v[54:55], v[130:131]
	v_pk_fma_f32 v[76:77], v[58:59], s[90:91], v[56:57] op_sel_hi:[1,0,1]
	v_pk_fma_f32 v[74:75], v[60:61], s[90:91], v[54:55] op_sel_hi:[1,0,1]
	s_nop 0
	global_load_dwordx4 v[130:133], v[214:215], off offset:512
	v_cvt_f32_f16_e32 v54, v217
	v_cvt_f32_f16_sdwa v55, v217 dst_sel:DWORD dst_unused:UNUSED_PAD src0_sel:WORD_1
	v_cvt_f32_f16_e32 v56, v216
	v_cvt_f32_f16_sdwa v57, v216 dst_sel:DWORD dst_unused:UNUSED_PAD src0_sel:WORD_1
	s_waitcnt vmcnt(0)
	v_pk_mul_f32 v[58:59], v[72:73], v[132:133]
	v_pk_mul_f32 v[60:61], v[70:71], v[130:131]
	v_pk_fma_f32 v[64:65], v[54:55], s[90:91], v[58:59] op_sel_hi:[1,0,1]
	v_pk_fma_f32 v[62:63], v[56:57], s[90:91], v[60:61] op_sel_hi:[1,0,1]
	v_cvt_f32_f16_e32 v54, v177
	v_cvt_f32_f16_sdwa v55, v177 dst_sel:DWORD dst_unused:UNUSED_PAD src0_sel:WORD_1
	v_cvt_f32_f16_e32 v56, v176
	v_cvt_f32_f16_sdwa v57, v176 dst_sel:DWORD dst_unused:UNUSED_PAD src0_sel:WORD_1
	v_pk_mul_f32 v[58:59], v[68:69], v[132:133]
	v_pk_mul_f32 v[60:61], v[66:67], v[130:131]
	v_pk_fma_f32 v[72:73], v[54:55], s[90:91], v[58:59] op_sel_hi:[1,0,1]
	v_pk_fma_f32 v[70:71], v[56:57], s[90:91], v[60:61] op_sel_hi:[1,0,1]
	v_cvt_f32_f16_e32 v54, v175
	v_cvt_f32_f16_sdwa v55, v175 dst_sel:DWORD dst_unused:UNUSED_PAD src0_sel:WORD_1
	v_cvt_f32_f16_e32 v56, v174
	v_cvt_f32_f16_sdwa v57, v174 dst_sel:DWORD dst_unused:UNUSED_PAD src0_sel:WORD_1
	v_pk_mul_f32 v[52:53], v[52:53], v[132:133]
	v_pk_mul_f32 v[50:51], v[50:51], v[130:131]
	v_pk_fma_f32 v[68:69], v[54:55], s[90:91], v[52:53] op_sel_hi:[1,0,1]
	v_pk_fma_f32 v[66:67], v[56:57], s[90:91], v[50:51] op_sel_hi:[1,0,1]
	v_cvt_f32_f16_e32 v50, v173
	v_cvt_f32_f16_sdwa v51, v173 dst_sel:DWORD dst_unused:UNUSED_PAD src0_sel:WORD_1
	v_cvt_f32_f16_e32 v52, v172
	v_cvt_f32_f16_sdwa v53, v172 dst_sel:DWORD dst_unused:UNUSED_PAD src0_sel:WORD_1
	v_pk_mul_f32 v[48:49], v[48:49], v[132:133]
	v_pk_mul_f32 v[46:47], v[46:47], v[130:131]
	v_pk_fma_f32 v[60:61], v[50:51], s[90:91], v[48:49] op_sel_hi:[1,0,1]
	v_pk_fma_f32 v[58:59], v[52:53], s[90:91], v[46:47] op_sel_hi:[1,0,1]
	v_cvt_f32_f16_e32 v46, v171
	v_cvt_f32_f16_sdwa v47, v171 dst_sel:DWORD dst_unused:UNUSED_PAD src0_sel:WORD_1
	v_cvt_f32_f16_e32 v48, v170
	v_cvt_f32_f16_sdwa v49, v170 dst_sel:DWORD dst_unused:UNUSED_PAD src0_sel:WORD_1
	v_pk_mul_f32 v[40:41], v[40:41], v[132:133]
	v_pk_mul_f32 v[38:39], v[38:39], v[130:131]
	v_pk_fma_f32 v[56:57], v[46:47], s[90:91], v[40:41] op_sel_hi:[1,0,1]
	v_pk_fma_f32 v[54:55], v[48:49], s[90:91], v[38:39] op_sel_hi:[1,0,1]
	v_cvt_f32_f16_e32 v38, v169
	v_cvt_f32_f16_sdwa v39, v169 dst_sel:DWORD dst_unused:UNUSED_PAD src0_sel:WORD_1
	v_cvt_f32_f16_e32 v40, v168
	v_cvt_f32_f16_sdwa v41, v168 dst_sel:DWORD dst_unused:UNUSED_PAD src0_sel:WORD_1
	v_pk_mul_f32 v[36:37], v[36:37], v[132:133]
	v_pk_mul_f32 v[34:35], v[34:35], v[130:131]
	v_pk_fma_f32 v[52:53], v[38:39], s[90:91], v[36:37] op_sel_hi:[1,0,1]
	v_pk_fma_f32 v[50:51], v[40:41], s[90:91], v[34:35] op_sel_hi:[1,0,1]
	v_cvt_f32_f16_e32 v34, v167
	v_cvt_f32_f16_sdwa v35, v167 dst_sel:DWORD dst_unused:UNUSED_PAD src0_sel:WORD_1
	v_cvt_f32_f16_e32 v36, v166
	v_cvt_f32_f16_sdwa v37, v166 dst_sel:DWORD dst_unused:UNUSED_PAD src0_sel:WORD_1
	v_pk_mul_f32 v[20:21], v[20:21], v[132:133]
	v_pk_mul_f32 v[18:19], v[18:19], v[130:131]
	v_pk_fma_f32 v[48:49], v[34:35], s[90:91], v[20:21] op_sel_hi:[1,0,1]
	v_pk_fma_f32 v[46:47], v[36:37], s[90:91], v[18:19] op_sel_hi:[1,0,1]
	v_cvt_f32_f16_e32 v18, v165
	v_cvt_f32_f16_sdwa v19, v165 dst_sel:DWORD dst_unused:UNUSED_PAD src0_sel:WORD_1
	v_cvt_f32_f16_e32 v20, v164
	v_cvt_f32_f16_sdwa v21, v164 dst_sel:DWORD dst_unused:UNUSED_PAD src0_sel:WORD_1
	v_pk_mul_f32 v[12:13], v[12:13], v[132:133]
	v_pk_mul_f32 v[10:11], v[10:11], v[130:131]
	v_pk_fma_f32 v[40:41], v[18:19], s[90:91], v[12:13] op_sel_hi:[1,0,1]
	v_pk_fma_f32 v[38:39], v[20:21], s[90:91], v[10:11] op_sel_hi:[1,0,1]
	s_nop 0
	global_load_dwordx4 v[130:133], v[214:215], off offset:576
	v_cvt_f32_f16_e32 v10, v163
	v_cvt_f32_f16_sdwa v11, v163 dst_sel:DWORD dst_unused:UNUSED_PAD src0_sel:WORD_1
	v_cvt_f32_f16_e32 v12, v162
	v_cvt_f32_f16_sdwa v13, v162 dst_sel:DWORD dst_unused:UNUSED_PAD src0_sel:WORD_1
	v_and_b32_e32 v163, 64, v249
	v_xor_b32_e32 v162, 16, v249
	v_add_u32_e32 v163, 64, v163
	v_cmp_lt_i32_e32 vcc, v162, v163
	v_xor_b32_e32 v164, 32, v249
	v_mov_b32_e32 v165, v152
	v_cndmask_b32_e32 v162, v249, v162, vcc
	v_cmp_lt_i32_e32 vcc, v164, v163
	v_mov_b32_e32 v166, v150
	v_mov_b32_e32 v167, v153
	v_cndmask_b32_e32 v163, v249, v164, vcc
	v_mov_b32_e32 v164, v151
	v_pk_add_f32 v[164:165], v[164:165], v[166:167]
	v_mov_b32_e32 v166, v103
	v_mov_b32_e32 v167, v104
	v_mov_b32_e32 v168, v102
	v_mov_b32_e32 v169, v105
	v_pk_add_f32 v[166:167], v[166:167], v[168:169]
	v_add_f32_e32 v164, v164, v165
	v_pk_add_f32 v[166:167], v[166:167], v[166:167] op_sel:[0,1] op_sel_hi:[1,0]
	v_add_f32_e32 v164, 0, v164
	v_add_f32_e32 v168, v62, v63
	v_add_f32_e32 v170, v64, v65
	v_lshlrev_b32_e32 v162, 2, v162
	v_lshlrev_b32_e32 v163, 2, v163
	v_cmp_gt_u32_e32 vcc, 16, v0
	s_waitcnt vmcnt(0)
	v_pk_mul_f32 v[20:21], v[128:129], v[132:133]
	v_pk_mul_f32 v[18:19], v[126:127], v[130:131]
	v_pk_fma_f32 v[20:21], v[10:11], s[90:91], v[20:21] op_sel_hi:[1,0,1]
	v_pk_fma_f32 v[18:19], v[12:13], s[90:91], v[18:19] op_sel_hi:[1,0,1]
	v_cvt_f32_f16_e32 v12, v161
	v_cvt_f32_f16_sdwa v13, v161 dst_sel:DWORD dst_unused:UNUSED_PAD src0_sel:WORD_1
	v_cvt_f32_f16_e32 v10, v160
	v_cvt_f32_f16_sdwa v11, v160 dst_sel:DWORD dst_unused:UNUSED_PAD src0_sel:WORD_1
	v_pk_mul_f32 v[34:35], v[44:45], v[132:133]
	v_pk_mul_f32 v[36:37], v[42:43], v[130:131]
	v_pk_fma_f32 v[12:13], v[12:13], s[90:91], v[34:35] op_sel_hi:[1,0,1]
	v_pk_fma_f32 v[10:11], v[10:11], s[90:91], v[36:37] op_sel_hi:[1,0,1]
	v_cvt_f32_f16_e32 v34, v157
	v_cvt_f32_f16_sdwa v35, v157 dst_sel:DWORD dst_unused:UNUSED_PAD src0_sel:WORD_1
	v_cvt_f32_f16_e32 v36, v156
	v_cvt_f32_f16_sdwa v37, v156 dst_sel:DWORD dst_unused:UNUSED_PAD src0_sel:WORD_1
	v_pk_mul_f32 v[32:33], v[32:33], v[132:133]
	v_pk_mul_f32 v[30:31], v[30:31], v[130:131]
	v_pk_fma_f32 v[44:45], v[34:35], s[90:91], v[32:33] op_sel_hi:[1,0,1]
	v_pk_fma_f32 v[42:43], v[36:37], s[90:91], v[30:31] op_sel_hi:[1,0,1]
	v_cvt_f32_f16_e32 v30, v155
	v_cvt_f32_f16_sdwa v31, v155 dst_sel:DWORD dst_unused:UNUSED_PAD src0_sel:WORD_1
	v_cvt_f32_f16_e32 v32, v154
	v_cvt_f32_f16_sdwa v33, v154 dst_sel:DWORD dst_unused:UNUSED_PAD src0_sel:WORD_1
	v_pk_mul_f32 v[28:29], v[28:29], v[132:133]
	v_pk_mul_f32 v[26:27], v[26:27], v[130:131]
	v_pk_fma_f32 v[36:37], v[30:31], s[90:91], v[28:29] op_sel_hi:[1,0,1]
	v_pk_fma_f32 v[34:35], v[32:33], s[90:91], v[26:27] op_sel_hi:[1,0,1]
	v_cvt_f32_f16_e32 v26, v145
	v_cvt_f32_f16_sdwa v27, v145 dst_sel:DWORD dst_unused:UNUSED_PAD src0_sel:WORD_1
	v_cvt_f32_f16_e32 v28, v144
	v_cvt_f32_f16_sdwa v29, v144 dst_sel:DWORD dst_unused:UNUSED_PAD src0_sel:WORD_1
	v_pk_mul_f32 v[24:25], v[24:25], v[132:133]
	v_pk_mul_f32 v[22:23], v[22:23], v[130:131]
	v_pk_fma_f32 v[32:33], v[26:27], s[90:91], v[24:25] op_sel_hi:[1,0,1]
	v_pk_fma_f32 v[30:31], v[28:29], s[90:91], v[22:23] op_sel_hi:[1,0,1]
	v_cvt_f32_f16_e32 v22, v143
	v_cvt_f32_f16_sdwa v23, v143 dst_sel:DWORD dst_unused:UNUSED_PAD src0_sel:WORD_1
	v_cvt_f32_f16_e32 v24, v142
	v_cvt_f32_f16_sdwa v25, v142 dst_sel:DWORD dst_unused:UNUSED_PAD src0_sel:WORD_1
	v_pk_mul_f32 v[16:17], v[16:17], v[132:133]
	v_pk_mul_f32 v[14:15], v[14:15], v[130:131]
	v_pk_fma_f32 v[28:29], v[22:23], s[90:91], v[16:17] op_sel_hi:[1,0,1]
	v_pk_fma_f32 v[26:27], v[24:25], s[90:91], v[14:15] op_sel_hi:[1,0,1]
	v_cvt_f32_f16_e32 v14, v141
	v_cvt_f32_f16_sdwa v15, v141 dst_sel:DWORD dst_unused:UNUSED_PAD src0_sel:WORD_1
	v_cvt_f32_f16_e32 v16, v140
	v_cvt_f32_f16_sdwa v17, v140 dst_sel:DWORD dst_unused:UNUSED_PAD src0_sel:WORD_1
	v_pk_mul_f32 v[8:9], v[8:9], v[132:133]
	v_pk_mul_f32 v[6:7], v[6:7], v[130:131]
	v_pk_fma_f32 v[8:9], v[14:15], s[90:91], v[8:9] op_sel_hi:[1,0,1]
	v_pk_fma_f32 v[6:7], v[16:17], s[90:91], v[6:7] op_sel_hi:[1,0,1]
	v_cvt_f32_f16_e32 v14, v139
	v_cvt_f32_f16_sdwa v15, v139 dst_sel:DWORD dst_unused:UNUSED_PAD src0_sel:WORD_1
	v_cvt_f32_f16_e32 v16, v138
	v_cvt_f32_f16_sdwa v17, v138 dst_sel:DWORD dst_unused:UNUSED_PAD src0_sel:WORD_1
	v_pk_mul_f32 v[4:5], v[4:5], v[132:133]
	v_pk_mul_f32 v[2:3], v[2:3], v[130:131]
	v_pk_fma_f32 v[4:5], v[14:15], s[90:91], v[4:5] op_sel_hi:[1,0,1]
	v_pk_fma_f32 v[2:3], v[16:17], s[90:91], v[2:3] op_sel_hi:[1,0,1]
	s_nop 0
	v_lshl_add_u64 v[14:15], s[22:23], 0, v[158:159]
	v_lshl_add_u64 v[22:23], s[6:7], 0, v[158:159]
	global_load_dwordx4 v[154:157], v[14:15], off
	global_load_dwordx4 v[158:161], v[22:23], off
	global_load_dwordx4 v[138:141], v[14:15], off offset:64
	global_load_dwordx4 v[142:145], v[22:23], off offset:64
	global_load_dwordx4 v[126:129], v[14:15], off offset:512
	global_load_dwordx4 v[130:133], v[22:23], off offset:512
	s_nop 0
	global_load_dwordx4 v[14:17], v[14:15], off offset:576
	s_nop 0
	global_load_dwordx4 v[22:25], v[22:23], off offset:576
	v_mov_b32_e32 v165, v18
	v_mov_b32_e32 v167, v19
	v_mov_b32_e32 v169, v20
	v_mov_b32_e32 v171, v21
	v_pk_add_f32 v[164:165], v[164:165], v[166:167]
	v_pk_add_f32 v[166:167], v[168:169], v[170:171]
	s_nop 0
	v_pk_add_f32 v[164:165], v[164:165], v[166:167]
	s_nop 0
	v_add_f32_e32 v164, v164, v165
	v_mov_b32_e32 v165, v164
	s_nop 1
	v_permlane16_swap_b32_e32 v165, v164
	s_waitcnt lgkmcnt(0)
	v_add_f32_e32 v164, v164, v165
	v_mov_b32_e32 v165, v164
	s_nop 1
	v_permlane32_swap_b32_e32 v165, v164
	s_waitcnt lgkmcnt(0)
	v_add_f32_e32 v164, v164, v165
	v_fmamk_f32 v166, v164, 0xbc800000, v153
	v_fmamk_f32 v168, v164, 0xbc800000, v151
	v_fmamk_f32 v165, v164, 0xbc800000, v152
	v_fmamk_f32 v167, v164, 0xbc800000, v150
	v_mul_f32_e32 v168, v168, v168
	v_mul_f32_e32 v166, v166, v166
	v_fmac_f32_e32 v168, v167, v167
	v_fmac_f32_e32 v166, v165, v165
	v_fmamk_f32 v167, v164, 0xbc800000, v105
	v_fmamk_f32 v169, v164, 0xbc800000, v103
	v_add_f32_e32 v165, v168, v166
	v_fmamk_f32 v166, v164, 0xbc800000, v104
	v_fmamk_f32 v168, v164, 0xbc800000, v102
	v_mul_f32_e32 v169, v169, v169
	v_mul_f32_e32 v167, v167, v167
	v_fmac_f32_e32 v169, v168, v168
	v_fmac_f32_e32 v167, v166, v166
	v_add_f32_e32 v166, v169, v167
	v_fmamk_f32 v167, v164, 0xbc800000, v65
	v_fmamk_f32 v169, v164, 0xbc800000, v63
	v_add_f32_e32 v165, v165, v166
	v_fmamk_f32 v166, v164, 0xbc800000, v64
	v_fmamk_f32 v168, v164, 0xbc800000, v62
	v_mul_f32_e32 v169, v169, v169
	v_mul_f32_e32 v167, v167, v167
	v_fmac_f32_e32 v169, v168, v168
	v_fmac_f32_e32 v167, v166, v166
	v_add_f32_e32 v166, v169, v167
	v_fmamk_f32 v167, v164, 0xbc800000, v21
	v_fmamk_f32 v169, v164, 0xbc800000, v19
	v_add_f32_e32 v165, v166, v165
	v_fmamk_f32 v166, v164, 0xbc800000, v20
	v_fmamk_f32 v168, v164, 0xbc800000, v18
	v_mul_f32_e32 v169, v169, v169
	v_mul_f32_e32 v167, v167, v167
	v_fmac_f32_e32 v169, v168, v168
	v_fmac_f32_e32 v167, v166, v166
	v_add_f32_e32 v166, v169, v167
	v_add_f32_e32 v165, v166, v165
	v_mov_b32_e32 v166, v165
	s_nop 1
	v_permlane16_swap_b32_e32 v166, v165
	s_waitcnt lgkmcnt(0)
	v_add_f32_e32 v165, v165, v166
	v_mov_b32_e32 v166, v165
	s_nop 1
	v_permlane32_swap_b32_e32 v166, v165
	s_and_saveexec_b64 s[6:7], vcc
	s_cbranch_execz .LBB0_1175
	s_lshl_b32 s9, s68, 11
	s_add_i32 s9, s2, s9
	v_mul_f32_e32 v164, 0x3c800000, v164
	v_lshl_add_u32 v167, v0, 5, s9
	s_waitcnt lgkmcnt(0)
	v_add_f32_e32 v165, v165, v166
	ds_write_b64 v167, v[164:165]
